# merge GEMM mid rescale: counted vmcnt waits per quarter (quarter q+1 loads stay in flight while quarter q is rescaled)
# speedup vs baseline: 1.0023x; 1.0023x over previous
.LBB0_3766:
	s_cmpk_eq_i32 s20, 0x1000
	s_cselect_b32 s22, 0, 16
	s_add_i32 s22, s53, s22
	v_mov_b32_e32 v2, v183
	v_mov_b32_e32 v4, v182
	s_ashr_i32 s23, s22, 31
	s_lshl_b64 s[22:23], s[22:23], 16
	v_lshl_add_u32 v2, v2, 4, v4
	s_add_u32 s24, s36, s22
	v_add_u32_e32 v4, s39, v2
	s_addc_u32 s25, s37, s23
	s_add_u32 s22, s24, 0x100000
	v_ashrrev_i32_e32 v5, 31, v4
	s_addc_u32 s23, s25, 0
	v_lshlrev_b64 v[134:135], 4, v[4:5]
	v_lshl_add_u64 v[136:137], s[24:25], 0, v[134:135]
	v_lshl_add_u64 v[134:135], s[22:23], 0, v[134:135]
	global_load_dwordx4 v[158:161], v[136:137], off nt
	global_load_dwordx4 v[162:165], v[134:135], off nt
	v_add_u32_e32 v4, 0x200, v4
	v_ashrrev_i32_e32 v5, 31, v4
	v_lshlrev_b64 v[4:5], 4, v[4:5]
	v_lshl_add_u64 v[134:135], s[24:25], 0, v[4:5]
	v_lshl_add_u64 v[4:5], s[22:23], 0, v[4:5]
	global_load_dwordx4 v[150:153], v[134:135], off nt
	global_load_dwordx4 v[154:157], v[4:5], off nt
	v_add_u32_e32 v4, s40, v2
	v_ashrrev_i32_e32 v5, 31, v4
	v_lshlrev_b64 v[4:5], 4, v[4:5]
	v_lshl_add_u64 v[134:135], s[24:25], 0, v[4:5]
	v_lshl_add_u64 v[4:5], s[22:23], 0, v[4:5]
	global_load_dwordx4 v[142:145], v[134:135], off nt
	global_load_dwordx4 v[146:149], v[4:5], off nt
	v_add_u32_e32 v4, s42, v2
	v_ashrrev_i32_e32 v5, 31, v4
	v_lshlrev_b64 v[4:5], 4, v[4:5]
	v_lshl_add_u64 v[134:135], s[24:25], 0, v[4:5]
	v_lshl_add_u64 v[4:5], s[22:23], 0, v[4:5]
	global_load_dwordx4 v[134:137], v[134:135], off nt
	s_andn2_b64 vcc, exec, s[8:9]
	global_load_dwordx4 v[138:141], v[4:5], off nt
	s_waitcnt vmcnt(4)
	v_cvt_f32_ubyte1_e32 v191, v158
	v_cvt_f32_ubyte0_e32 v4, v162
	v_cvt_f32_ubyte1_e32 v5, v162
	v_rcp_iflag_f32_e32 v4, v4
	v_rcp_iflag_f32_e32 v5, v5
	v_cvt_f32_ubyte0_e32 v190, v158
	v_cvt_f32_ubyte2_e32 v186, v162
	v_cvt_f32_ubyte3_e32 v162, v162
	v_pk_mul_f32 v[4:5], v[4:5], v[190:191]
	v_rcp_iflag_f32_e32 v186, v186
	v_rcp_iflag_f32_e32 v187, v162
	v_pk_mul_f32 v[130:131], v[130:131], v[4:5]
	v_cvt_f32_ubyte0_e32 v4, v163
	v_cvt_f32_ubyte1_e32 v5, v163
	v_rcp_iflag_f32_e32 v4, v4
	v_rcp_iflag_f32_e32 v5, v5
	v_cvt_f32_ubyte3_e32 v189, v158
	v_cvt_f32_ubyte2_e32 v188, v158
	v_cvt_f32_ubyte2_e32 v158, v163
	v_pk_mul_f32 v[186:187], v[186:187], v[188:189]
	v_rcp_iflag_f32_e32 v162, v158
	v_cvt_f32_ubyte3_e32 v158, v163
	v_cvt_f32_ubyte1_e32 v189, v159
	v_cvt_f32_ubyte0_e32 v188, v159
	v_rcp_iflag_f32_e32 v163, v158
	v_pk_mul_f32 v[4:5], v[4:5], v[188:189]
	v_pk_mul_f32 v[132:133], v[132:133], v[186:187]
	v_pk_mul_f32 v[126:127], v[126:127], v[4:5]
	v_cvt_f32_ubyte0_e32 v4, v164
	v_cvt_f32_ubyte1_e32 v5, v164
	v_rcp_iflag_f32_e32 v4, v4
	v_rcp_iflag_f32_e32 v5, v5
	v_cvt_f32_ubyte3_e32 v187, v159
	v_cvt_f32_ubyte2_e32 v186, v159
	v_pk_mul_f32 v[158:159], v[162:163], v[186:187]
	v_cvt_f32_ubyte1_e32 v187, v160
	v_pk_mul_f32 v[128:129], v[128:129], v[158:159]
	v_cvt_f32_ubyte2_e32 v158, v164
	v_cvt_f32_ubyte3_e32 v159, v164
	v_cvt_f32_ubyte0_e32 v186, v160
	v_rcp_iflag_f32_e32 v158, v158
	v_rcp_iflag_f32_e32 v159, v159
	v_pk_mul_f32 v[4:5], v[4:5], v[186:187]
	v_cvt_f32_ubyte3_e32 v163, v160
	v_pk_mul_f32 v[122:123], v[122:123], v[4:5]
	v_cvt_f32_ubyte0_e32 v4, v165
	v_cvt_f32_ubyte1_e32 v5, v165
	v_rcp_iflag_f32_e32 v4, v4
	v_rcp_iflag_f32_e32 v5, v5
	v_cvt_f32_ubyte2_e32 v162, v160
	v_pk_mul_f32 v[158:159], v[158:159], v[162:163]
	v_cvt_f32_ubyte0_e32 v164, v161
	v_pk_mul_f32 v[124:125], v[124:125], v[158:159]
	v_cvt_f32_ubyte2_e32 v158, v165
	v_cvt_f32_ubyte3_e32 v159, v165
	v_cvt_f32_ubyte1_e32 v165, v161
	v_pk_mul_f32 v[4:5], v[4:5], v[164:165]
	v_rcp_iflag_f32_e32 v158, v158
	v_rcp_iflag_f32_e32 v159, v159
	v_pk_mul_f32 v[118:119], v[118:119], v[4:5]
	v_cvt_f32_ubyte0_e32 v4, v154
	v_cvt_f32_ubyte1_e32 v5, v154
	v_rcp_iflag_f32_e32 v4, v4
	v_rcp_iflag_f32_e32 v5, v5
	v_cvt_f32_ubyte3_e32 v163, v161
	v_cvt_f32_ubyte2_e32 v162, v161
	v_pk_mul_f32 v[158:159], v[158:159], v[162:163]
	v_cvt_f32_ubyte1_e32 v163, v150
	v_cvt_f32_ubyte0_e32 v162, v150
	v_pk_mul_f32 v[120:121], v[120:121], v[158:159]
	v_cvt_f32_ubyte2_e32 v158, v154
	v_cvt_f32_ubyte3_e32 v154, v154
	v_pk_mul_f32 v[4:5], v[4:5], v[162:163]
	v_rcp_iflag_f32_e32 v158, v158
	v_rcp_iflag_f32_e32 v159, v154
	v_pk_mul_f32 v[114:115], v[114:115], v[4:5]
	v_cvt_f32_ubyte0_e32 v4, v155
	v_cvt_f32_ubyte1_e32 v5, v155
	v_rcp_iflag_f32_e32 v4, v4
	v_rcp_iflag_f32_e32 v5, v5
	v_cvt_f32_ubyte3_e32 v161, v150
	v_cvt_f32_ubyte2_e32 v160, v150
	v_cvt_f32_ubyte2_e32 v150, v155
	v_rcp_iflag_f32_e32 v154, v150
	v_cvt_f32_ubyte3_e32 v150, v155
	v_pk_mul_f32 v[158:159], v[158:159], v[160:161]
	v_rcp_iflag_f32_e32 v155, v150
	v_cvt_f32_ubyte1_e32 v161, v151
	v_cvt_f32_ubyte0_e32 v160, v151
	v_pk_mul_f32 v[4:5], v[4:5], v[160:161]
	v_pk_mul_f32 v[116:117], v[116:117], v[158:159]
	v_pk_mul_f32 v[110:111], v[110:111], v[4:5]
	v_cvt_f32_ubyte0_e32 v4, v156
	v_cvt_f32_ubyte1_e32 v5, v156
	v_cvt_f32_ubyte3_e32 v159, v151
	v_cvt_f32_ubyte2_e32 v158, v151
	v_rcp_iflag_f32_e32 v4, v4
	v_rcp_iflag_f32_e32 v5, v5
	v_pk_mul_f32 v[150:151], v[154:155], v[158:159]
	v_cvt_f32_ubyte1_e32 v159, v152
	v_pk_mul_f32 v[112:113], v[112:113], v[150:151]
	v_cvt_f32_ubyte2_e32 v150, v156
	v_cvt_f32_ubyte3_e32 v151, v156
	v_rcp_iflag_f32_e32 v150, v150
	v_rcp_iflag_f32_e32 v151, v151
	v_cvt_f32_ubyte0_e32 v158, v152
	v_pk_mul_f32 v[4:5], v[4:5], v[158:159]
	v_cvt_f32_ubyte3_e32 v155, v152
	v_pk_mul_f32 v[106:107], v[106:107], v[4:5]
	v_cvt_f32_ubyte0_e32 v4, v157
	v_cvt_f32_ubyte1_e32 v5, v157
	v_cvt_f32_ubyte2_e32 v154, v152
	v_rcp_iflag_f32_e32 v4, v4
	v_rcp_iflag_f32_e32 v5, v5
	v_pk_mul_f32 v[150:151], v[150:151], v[154:155]
	v_cvt_f32_ubyte0_e32 v156, v153
	v_pk_mul_f32 v[108:109], v[108:109], v[150:151]
	v_cvt_f32_ubyte2_e32 v150, v157
	v_cvt_f32_ubyte3_e32 v151, v157
	v_rcp_iflag_f32_e32 v150, v150
	v_rcp_iflag_f32_e32 v151, v151
	v_cvt_f32_ubyte1_e32 v157, v153
	v_pk_mul_f32 v[4:5], v[4:5], v[156:157]
	v_cvt_f32_ubyte3_e32 v155, v153
	v_pk_mul_f32 v[102:103], v[102:103], v[4:5]
	v_add_u32_e32 v4, s43, v2
	v_cvt_f32_ubyte2_e32 v154, v153
	v_ashrrev_i32_e32 v5, 31, v4
	v_pk_mul_f32 v[150:151], v[150:151], v[154:155]
	v_lshlrev_b64 v[4:5], 4, v[4:5]
	v_pk_mul_f32 v[104:105], v[104:105], v[150:151]
	v_lshl_add_u64 v[150:151], s[24:25], 0, v[4:5]
	v_lshl_add_u64 v[4:5], s[22:23], 0, v[4:5]
	global_load_dwordx4 v[158:161], v[150:151], off nt
	global_load_dwordx4 v[162:165], v[4:5], off nt
	v_add_u32_e32 v4, s44, v2
	v_ashrrev_i32_e32 v5, 31, v4
	v_lshlrev_b64 v[4:5], 4, v[4:5]
	v_lshl_add_u64 v[150:151], s[24:25], 0, v[4:5]
	v_lshl_add_u64 v[4:5], s[22:23], 0, v[4:5]
	global_load_dwordx4 v[150:153], v[150:151], off nt
	s_waitcnt vmcnt(3)
	v_cvt_f32_ubyte1_e32 v191, v142
	global_load_dwordx4 v[154:157], v[4:5], off nt
	v_cvt_f32_ubyte0_e32 v4, v146
	v_cvt_f32_ubyte1_e32 v5, v146
	v_rcp_iflag_f32_e32 v4, v4
	v_rcp_iflag_f32_e32 v5, v5
	v_cvt_f32_ubyte0_e32 v190, v142
	v_cvt_f32_ubyte2_e32 v186, v146
	v_cvt_f32_ubyte3_e32 v146, v146
	v_pk_mul_f32 v[4:5], v[4:5], v[190:191]
	v_rcp_iflag_f32_e32 v186, v186
	v_rcp_iflag_f32_e32 v187, v146
	v_pk_mul_f32 v[98:99], v[98:99], v[4:5]
	v_cvt_f32_ubyte0_e32 v4, v147
	v_cvt_f32_ubyte1_e32 v5, v147
	v_rcp_iflag_f32_e32 v4, v4
	v_rcp_iflag_f32_e32 v5, v5
	v_cvt_f32_ubyte3_e32 v189, v142
	v_cvt_f32_ubyte2_e32 v188, v142
	v_cvt_f32_ubyte2_e32 v142, v147
	v_pk_mul_f32 v[186:187], v[186:187], v[188:189]
	v_rcp_iflag_f32_e32 v146, v142
	v_cvt_f32_ubyte3_e32 v142, v147
	v_cvt_f32_ubyte1_e32 v189, v143
	v_cvt_f32_ubyte0_e32 v188, v143
	v_rcp_iflag_f32_e32 v147, v142
	v_pk_mul_f32 v[4:5], v[4:5], v[188:189]
	v_pk_mul_f32 v[100:101], v[100:101], v[186:187]
	v_pk_mul_f32 v[94:95], v[94:95], v[4:5]
	v_cvt_f32_ubyte0_e32 v4, v148
	v_cvt_f32_ubyte1_e32 v5, v148
	v_rcp_iflag_f32_e32 v4, v4
	v_rcp_iflag_f32_e32 v5, v5
	v_cvt_f32_ubyte3_e32 v187, v143
	v_cvt_f32_ubyte2_e32 v186, v143
	v_pk_mul_f32 v[142:143], v[146:147], v[186:187]
	v_cvt_f32_ubyte1_e32 v187, v144
	v_pk_mul_f32 v[96:97], v[96:97], v[142:143]
	v_cvt_f32_ubyte2_e32 v142, v148
	v_cvt_f32_ubyte3_e32 v143, v148
	v_cvt_f32_ubyte0_e32 v186, v144
	v_rcp_iflag_f32_e32 v142, v142
	v_rcp_iflag_f32_e32 v143, v143
	v_pk_mul_f32 v[4:5], v[4:5], v[186:187]
	v_cvt_f32_ubyte3_e32 v147, v144
	v_pk_mul_f32 v[90:91], v[90:91], v[4:5]
	v_cvt_f32_ubyte0_e32 v4, v149
	v_cvt_f32_ubyte1_e32 v5, v149
	v_rcp_iflag_f32_e32 v4, v4
	v_rcp_iflag_f32_e32 v5, v5
	v_cvt_f32_ubyte2_e32 v146, v144
	v_pk_mul_f32 v[142:143], v[142:143], v[146:147]
	v_cvt_f32_ubyte0_e32 v148, v145
	v_pk_mul_f32 v[92:93], v[92:93], v[142:143]
	v_cvt_f32_ubyte2_e32 v142, v149
	v_cvt_f32_ubyte3_e32 v143, v149
	v_cvt_f32_ubyte1_e32 v149, v145
	v_pk_mul_f32 v[4:5], v[4:5], v[148:149]
	v_rcp_iflag_f32_e32 v142, v142
	v_rcp_iflag_f32_e32 v143, v143
	v_pk_mul_f32 v[86:87], v[86:87], v[4:5]
	v_cvt_f32_ubyte0_e32 v4, v138
	v_cvt_f32_ubyte1_e32 v5, v138
	v_rcp_iflag_f32_e32 v4, v4
	v_rcp_iflag_f32_e32 v5, v5
	v_cvt_f32_ubyte3_e32 v147, v145
	v_cvt_f32_ubyte2_e32 v146, v145
	v_pk_mul_f32 v[142:143], v[142:143], v[146:147]
	v_cvt_f32_ubyte1_e32 v147, v134
	v_cvt_f32_ubyte0_e32 v146, v134
	v_pk_mul_f32 v[88:89], v[88:89], v[142:143]
	v_cvt_f32_ubyte2_e32 v142, v138
	v_cvt_f32_ubyte3_e32 v138, v138
	v_pk_mul_f32 v[4:5], v[4:5], v[146:147]
	v_rcp_iflag_f32_e32 v142, v142
	v_rcp_iflag_f32_e32 v143, v138
	v_pk_mul_f32 v[82:83], v[82:83], v[4:5]
	v_cvt_f32_ubyte0_e32 v4, v139
	v_cvt_f32_ubyte1_e32 v5, v139
	v_rcp_iflag_f32_e32 v4, v4
	v_rcp_iflag_f32_e32 v5, v5
	v_cvt_f32_ubyte3_e32 v145, v134
	v_cvt_f32_ubyte2_e32 v144, v134
	v_cvt_f32_ubyte2_e32 v134, v139
	v_rcp_iflag_f32_e32 v138, v134
	v_cvt_f32_ubyte3_e32 v134, v139
	v_pk_mul_f32 v[142:143], v[142:143], v[144:145]
	v_rcp_iflag_f32_e32 v139, v134
	v_cvt_f32_ubyte1_e32 v145, v135
	v_cvt_f32_ubyte0_e32 v144, v135
	v_pk_mul_f32 v[4:5], v[4:5], v[144:145]
	v_pk_mul_f32 v[84:85], v[84:85], v[142:143]
	v_pk_mul_f32 v[78:79], v[78:79], v[4:5]
	v_cvt_f32_ubyte0_e32 v4, v140
	v_cvt_f32_ubyte1_e32 v5, v140
	v_cvt_f32_ubyte3_e32 v143, v135
	v_cvt_f32_ubyte2_e32 v142, v135
	v_rcp_iflag_f32_e32 v4, v4
	v_rcp_iflag_f32_e32 v5, v5
	v_pk_mul_f32 v[134:135], v[138:139], v[142:143]
	v_cvt_f32_ubyte1_e32 v143, v136
	v_pk_mul_f32 v[80:81], v[80:81], v[134:135]
	v_cvt_f32_ubyte2_e32 v134, v140
	v_cvt_f32_ubyte3_e32 v135, v140
	v_rcp_iflag_f32_e32 v134, v134
	v_rcp_iflag_f32_e32 v135, v135
	v_cvt_f32_ubyte0_e32 v142, v136
	v_pk_mul_f32 v[4:5], v[4:5], v[142:143]
	v_cvt_f32_ubyte3_e32 v139, v136
	v_pk_mul_f32 v[74:75], v[74:75], v[4:5]
	v_cvt_f32_ubyte0_e32 v4, v141
	v_cvt_f32_ubyte1_e32 v5, v141
	v_cvt_f32_ubyte2_e32 v138, v136
	v_rcp_iflag_f32_e32 v4, v4
	v_rcp_iflag_f32_e32 v5, v5
	v_pk_mul_f32 v[134:135], v[134:135], v[138:139]
	v_cvt_f32_ubyte0_e32 v140, v137
	v_pk_mul_f32 v[76:77], v[76:77], v[134:135]
	v_cvt_f32_ubyte2_e32 v134, v141
	v_cvt_f32_ubyte3_e32 v135, v141
	v_rcp_iflag_f32_e32 v134, v134
	v_rcp_iflag_f32_e32 v135, v135
	v_cvt_f32_ubyte1_e32 v141, v137
	v_pk_mul_f32 v[4:5], v[4:5], v[140:141]
	v_cvt_f32_ubyte3_e32 v139, v137
	v_pk_mul_f32 v[70:71], v[70:71], v[4:5]
	v_add_u32_e32 v4, s45, v2
	v_cvt_f32_ubyte2_e32 v138, v137
	v_ashrrev_i32_e32 v5, 31, v4
	v_pk_mul_f32 v[134:135], v[134:135], v[138:139]
	v_lshlrev_b64 v[4:5], 4, v[4:5]
	v_pk_mul_f32 v[72:73], v[72:73], v[134:135]
	v_lshl_add_u64 v[134:135], s[24:25], 0, v[4:5]
	v_lshl_add_u64 v[4:5], s[22:23], 0, v[4:5]
	global_load_dwordx4 v[142:145], v[134:135], off nt
	global_load_dwordx4 v[146:149], v[4:5], off nt
	v_add_u32_e32 v4, s46, v2
	v_ashrrev_i32_e32 v5, 31, v4
	v_lshlrev_b64 v[4:5], 4, v[4:5]
	v_lshl_add_u64 v[134:135], s[24:25], 0, v[4:5]
	v_lshl_add_u64 v[4:5], s[22:23], 0, v[4:5]
	global_load_dwordx4 v[134:137], v[134:135], off nt
	s_waitcnt vmcnt(3)
	v_cvt_f32_ubyte0_e32 v2, v162
	global_load_dwordx4 v[138:141], v[4:5], off nt
	v_rcp_iflag_f32_e32 v4, v2
	v_cvt_f32_ubyte1_e32 v2, v162
	v_rcp_iflag_f32_e32 v5, v2
	v_cvt_f32_ubyte2_e32 v2, v162
	v_rcp_iflag_f32_e32 v186, v2
	v_cvt_f32_ubyte3_e32 v2, v162
	v_cvt_f32_ubyte1_e32 v191, v158
	v_cvt_f32_ubyte0_e32 v190, v158
	v_rcp_iflag_f32_e32 v187, v2
	v_pk_mul_f32 v[4:5], v[4:5], v[190:191]
	v_cvt_f32_ubyte0_e32 v2, v163
	v_pk_mul_f32 v[66:67], v[66:67], v[4:5]
	v_rcp_iflag_f32_e32 v4, v2
	v_cvt_f32_ubyte1_e32 v2, v163
	v_rcp_iflag_f32_e32 v5, v2
	v_cvt_f32_ubyte3_e32 v189, v158
	v_cvt_f32_ubyte2_e32 v188, v158
	v_cvt_f32_ubyte2_e32 v2, v163
	v_pk_mul_f32 v[186:187], v[186:187], v[188:189]
	v_rcp_iflag_f32_e32 v162, v2
	v_cvt_f32_ubyte3_e32 v2, v163
	v_cvt_f32_ubyte1_e32 v189, v159
	v_cvt_f32_ubyte0_e32 v188, v159
	v_rcp_iflag_f32_e32 v163, v2
	v_pk_mul_f32 v[4:5], v[4:5], v[188:189]
	v_cvt_f32_ubyte0_e32 v2, v164
	v_pk_mul_f32 v[62:63], v[62:63], v[4:5]
	v_rcp_iflag_f32_e32 v4, v2
	v_cvt_f32_ubyte1_e32 v2, v164
	v_rcp_iflag_f32_e32 v5, v2
	v_pk_mul_f32 v[68:69], v[68:69], v[186:187]
	v_cvt_f32_ubyte3_e32 v187, v159
	v_cvt_f32_ubyte2_e32 v186, v159
	v_pk_mul_f32 v[158:159], v[162:163], v[186:187]
	v_cvt_f32_ubyte2_e32 v2, v164
	v_pk_mul_f32 v[64:65], v[64:65], v[158:159]
	v_rcp_iflag_f32_e32 v158, v2
	v_cvt_f32_ubyte3_e32 v2, v164
	v_cvt_f32_ubyte1_e32 v187, v160
	v_cvt_f32_ubyte0_e32 v186, v160
	v_rcp_iflag_f32_e32 v159, v2
	v_pk_mul_f32 v[4:5], v[4:5], v[186:187]
	v_cvt_f32_ubyte0_e32 v2, v165
	v_pk_mul_f32 v[58:59], v[58:59], v[4:5]
	v_rcp_iflag_f32_e32 v4, v2
	v_cvt_f32_ubyte1_e32 v2, v165
	v_rcp_iflag_f32_e32 v5, v2
	v_cvt_f32_ubyte3_e32 v163, v160
	v_cvt_f32_ubyte2_e32 v162, v160
	v_pk_mul_f32 v[158:159], v[158:159], v[162:163]
	v_cvt_f32_ubyte2_e32 v2, v165
	v_pk_mul_f32 v[60:61], v[60:61], v[158:159]
	v_rcp_iflag_f32_e32 v158, v2
	v_cvt_f32_ubyte3_e32 v2, v165
	v_cvt_f32_ubyte1_e32 v165, v161
	v_cvt_f32_ubyte0_e32 v164, v161
	v_rcp_iflag_f32_e32 v159, v2
	v_pk_mul_f32 v[4:5], v[4:5], v[164:165]
	v_cvt_f32_ubyte0_e32 v2, v154
	v_pk_mul_f32 v[54:55], v[54:55], v[4:5]
	v_rcp_iflag_f32_e32 v4, v2
	v_cvt_f32_ubyte1_e32 v2, v154
	v_rcp_iflag_f32_e32 v5, v2
	v_cvt_f32_ubyte3_e32 v163, v161
	v_cvt_f32_ubyte2_e32 v162, v161
	v_pk_mul_f32 v[158:159], v[158:159], v[162:163]
	v_cvt_f32_ubyte2_e32 v2, v154
	v_pk_mul_f32 v[56:57], v[56:57], v[158:159]
	v_rcp_iflag_f32_e32 v158, v2
	v_cvt_f32_ubyte3_e32 v2, v154
	v_cvt_f32_ubyte1_e32 v163, v150
	v_cvt_f32_ubyte0_e32 v162, v150
	v_rcp_iflag_f32_e32 v159, v2
	v_pk_mul_f32 v[4:5], v[4:5], v[162:163]
	v_cvt_f32_ubyte0_e32 v2, v155
	v_pk_mul_f32 v[50:51], v[50:51], v[4:5]
	v_rcp_iflag_f32_e32 v4, v2
	v_cvt_f32_ubyte1_e32 v2, v155
	v_rcp_iflag_f32_e32 v5, v2
	v_cvt_f32_ubyte3_e32 v161, v150
	v_cvt_f32_ubyte2_e32 v160, v150
	v_cvt_f32_ubyte2_e32 v2, v155
	v_pk_mul_f32 v[158:159], v[158:159], v[160:161]
	v_rcp_iflag_f32_e32 v154, v2
	v_cvt_f32_ubyte3_e32 v2, v155
	v_cvt_f32_ubyte1_e32 v161, v151
	v_cvt_f32_ubyte0_e32 v160, v151
	v_rcp_iflag_f32_e32 v155, v2
	v_pk_mul_f32 v[4:5], v[4:5], v[160:161]
	v_cvt_f32_ubyte0_e32 v2, v156
	v_pk_mul_f32 v[46:47], v[46:47], v[4:5]
	v_rcp_iflag_f32_e32 v4, v2
	v_cvt_f32_ubyte1_e32 v2, v156
	v_rcp_iflag_f32_e32 v5, v2
	v_pk_mul_f32 v[52:53], v[52:53], v[158:159]
	v_cvt_f32_ubyte3_e32 v159, v151
	v_cvt_f32_ubyte2_e32 v158, v151
	v_pk_mul_f32 v[150:151], v[154:155], v[158:159]
	v_cvt_f32_ubyte2_e32 v2, v156
	v_pk_mul_f32 v[48:49], v[48:49], v[150:151]
	v_rcp_iflag_f32_e32 v150, v2
	v_cvt_f32_ubyte3_e32 v2, v156
	v_cvt_f32_ubyte1_e32 v159, v152
	v_cvt_f32_ubyte0_e32 v158, v152
	v_rcp_iflag_f32_e32 v151, v2
	v_pk_mul_f32 v[4:5], v[4:5], v[158:159]
	v_cvt_f32_ubyte0_e32 v2, v157
	v_pk_mul_f32 v[42:43], v[42:43], v[4:5]
	v_rcp_iflag_f32_e32 v4, v2
	v_cvt_f32_ubyte1_e32 v2, v157
	v_rcp_iflag_f32_e32 v5, v2
	v_cvt_f32_ubyte3_e32 v155, v152
	v_cvt_f32_ubyte2_e32 v154, v152
	v_pk_mul_f32 v[150:151], v[150:151], v[154:155]
	v_cvt_f32_ubyte2_e32 v2, v157
	v_pk_mul_f32 v[44:45], v[44:45], v[150:151]
	v_rcp_iflag_f32_e32 v150, v2
	v_cvt_f32_ubyte3_e32 v2, v157
	v_cvt_f32_ubyte1_e32 v157, v153
	v_cvt_f32_ubyte0_e32 v156, v153
	v_rcp_iflag_f32_e32 v151, v2
	v_pk_mul_f32 v[4:5], v[4:5], v[156:157]
	s_waitcnt vmcnt(1)
	v_cvt_f32_ubyte0_e32 v2, v146
	v_pk_mul_f32 v[38:39], v[38:39], v[4:5]
	v_rcp_iflag_f32_e32 v4, v2
	v_cvt_f32_ubyte1_e32 v2, v146
	v_rcp_iflag_f32_e32 v5, v2
	v_cvt_f32_ubyte3_e32 v155, v153
	v_cvt_f32_ubyte2_e32 v154, v153
	v_pk_mul_f32 v[150:151], v[150:151], v[154:155]
	v_cvt_f32_ubyte2_e32 v2, v146
	v_pk_mul_f32 v[40:41], v[40:41], v[150:151]
	v_rcp_iflag_f32_e32 v150, v2
	v_cvt_f32_ubyte3_e32 v2, v146
	v_cvt_f32_ubyte1_e32 v155, v142
	v_cvt_f32_ubyte0_e32 v154, v142
	v_rcp_iflag_f32_e32 v151, v2
	v_pk_mul_f32 v[4:5], v[4:5], v[154:155]
	v_cvt_f32_ubyte0_e32 v2, v147
	v_pk_mul_f32 v[34:35], v[34:35], v[4:5]
	v_rcp_iflag_f32_e32 v4, v2
	v_cvt_f32_ubyte1_e32 v2, v147
	v_rcp_iflag_f32_e32 v5, v2
	v_cvt_f32_ubyte3_e32 v153, v142
	v_cvt_f32_ubyte2_e32 v152, v142
	v_cvt_f32_ubyte2_e32 v2, v147
	v_pk_mul_f32 v[150:151], v[150:151], v[152:153]
	v_rcp_iflag_f32_e32 v146, v2
	v_cvt_f32_ubyte3_e32 v2, v147
	v_cvt_f32_ubyte1_e32 v153, v143
	v_cvt_f32_ubyte0_e32 v152, v143
	v_rcp_iflag_f32_e32 v147, v2
	v_pk_mul_f32 v[4:5], v[4:5], v[152:153]
	v_cvt_f32_ubyte0_e32 v2, v148
	v_pk_mul_f32 v[30:31], v[30:31], v[4:5]
	v_rcp_iflag_f32_e32 v4, v2
	v_cvt_f32_ubyte1_e32 v2, v148
	v_rcp_iflag_f32_e32 v5, v2
	v_pk_mul_f32 v[36:37], v[36:37], v[150:151]
	v_cvt_f32_ubyte3_e32 v151, v143
	v_cvt_f32_ubyte2_e32 v150, v143
	v_pk_mul_f32 v[142:143], v[146:147], v[150:151]
	v_cvt_f32_ubyte2_e32 v2, v148
	v_pk_mul_f32 v[32:33], v[32:33], v[142:143]
	v_rcp_iflag_f32_e32 v142, v2
	v_cvt_f32_ubyte3_e32 v2, v148
	v_cvt_f32_ubyte1_e32 v151, v144
	v_cvt_f32_ubyte0_e32 v150, v144
	v_rcp_iflag_f32_e32 v143, v2
	v_pk_mul_f32 v[4:5], v[4:5], v[150:151]
	v_cvt_f32_ubyte0_e32 v2, v149
	v_pk_mul_f32 v[26:27], v[26:27], v[4:5]
	v_rcp_iflag_f32_e32 v4, v2
	v_cvt_f32_ubyte1_e32 v2, v149
	v_rcp_iflag_f32_e32 v5, v2
	v_cvt_f32_ubyte3_e32 v147, v144
	v_cvt_f32_ubyte2_e32 v146, v144
	v_pk_mul_f32 v[142:143], v[142:143], v[146:147]
	v_cvt_f32_ubyte2_e32 v2, v149
	v_pk_mul_f32 v[28:29], v[28:29], v[142:143]
	v_rcp_iflag_f32_e32 v142, v2
	v_cvt_f32_ubyte3_e32 v2, v149
	v_cvt_f32_ubyte1_e32 v149, v145
	v_cvt_f32_ubyte0_e32 v148, v145
	v_rcp_iflag_f32_e32 v143, v2
	v_pk_mul_f32 v[4:5], v[4:5], v[148:149]
	s_waitcnt vmcnt(0)
	v_cvt_f32_ubyte0_e32 v2, v138
	v_pk_mul_f32 v[22:23], v[22:23], v[4:5]
	v_rcp_iflag_f32_e32 v4, v2
	v_cvt_f32_ubyte1_e32 v2, v138
	v_rcp_iflag_f32_e32 v5, v2
	v_cvt_f32_ubyte3_e32 v147, v145
	v_cvt_f32_ubyte2_e32 v146, v145
	v_pk_mul_f32 v[142:143], v[142:143], v[146:147]
	v_cvt_f32_ubyte2_e32 v2, v138
	v_pk_mul_f32 v[24:25], v[24:25], v[142:143]
	v_rcp_iflag_f32_e32 v142, v2
	v_cvt_f32_ubyte3_e32 v2, v138
	v_cvt_f32_ubyte1_e32 v147, v134
	v_cvt_f32_ubyte0_e32 v146, v134
	v_rcp_iflag_f32_e32 v143, v2
	v_pk_mul_f32 v[4:5], v[4:5], v[146:147]
	v_cvt_f32_ubyte0_e32 v2, v139
	v_pk_mul_f32 v[18:19], v[18:19], v[4:5]
	v_rcp_iflag_f32_e32 v4, v2
	v_cvt_f32_ubyte1_e32 v2, v139
	v_rcp_iflag_f32_e32 v5, v2
	v_cvt_f32_ubyte2_e32 v2, v139
	v_rcp_iflag_f32_e32 v138, v2
	v_cvt_f32_ubyte3_e32 v2, v139
	v_cvt_f32_ubyte3_e32 v145, v134
	v_cvt_f32_ubyte2_e32 v144, v134
	v_rcp_iflag_f32_e32 v139, v2
	v_pk_mul_f32 v[142:143], v[142:143], v[144:145]
	v_cvt_f32_ubyte1_e32 v145, v135
	v_cvt_f32_ubyte0_e32 v144, v135
	v_pk_mul_f32 v[4:5], v[4:5], v[144:145]
	v_cvt_f32_ubyte0_e32 v2, v140
	v_pk_mul_f32 v[20:21], v[20:21], v[142:143]
	v_cvt_f32_ubyte3_e32 v143, v135
	v_cvt_f32_ubyte2_e32 v142, v135
	v_pk_mul_f32 v[14:15], v[14:15], v[4:5]
	v_rcp_iflag_f32_e32 v4, v2
	v_cvt_f32_ubyte1_e32 v2, v140
	v_pk_mul_f32 v[134:135], v[138:139], v[142:143]
	v_rcp_iflag_f32_e32 v5, v2
	v_cvt_f32_ubyte2_e32 v2, v140
	v_pk_mul_f32 v[16:17], v[16:17], v[134:135]
	v_rcp_iflag_f32_e32 v134, v2
	v_cvt_f32_ubyte3_e32 v2, v140
	v_rcp_iflag_f32_e32 v135, v2
	v_cvt_f32_ubyte1_e32 v143, v136
	v_cvt_f32_ubyte0_e32 v142, v136
	v_pk_mul_f32 v[4:5], v[4:5], v[142:143]
	v_cvt_f32_ubyte0_e32 v2, v141
	v_cvt_f32_ubyte3_e32 v139, v136
	v_cvt_f32_ubyte2_e32 v138, v136
	v_pk_mul_f32 v[10:11], v[10:11], v[4:5]
	v_rcp_iflag_f32_e32 v4, v2
	v_cvt_f32_ubyte1_e32 v2, v141
	v_pk_mul_f32 v[134:135], v[134:135], v[138:139]
	v_rcp_iflag_f32_e32 v5, v2
	v_cvt_f32_ubyte2_e32 v2, v141
	v_pk_mul_f32 v[12:13], v[12:13], v[134:135]
	v_rcp_iflag_f32_e32 v134, v2
	v_cvt_f32_ubyte3_e32 v2, v141
	v_rcp_iflag_f32_e32 v135, v2
	v_cvt_f32_ubyte3_e32 v139, v137
	v_cvt_f32_ubyte2_e32 v138, v137
	v_cvt_f32_ubyte1_e32 v141, v137
	v_cvt_f32_ubyte0_e32 v140, v137
	v_pk_mul_f32 v[4:5], v[4:5], v[140:141]
	v_pk_mul_f32 v[134:135], v[134:135], v[138:139]
	v_pk_mul_f32 v[6:7], v[6:7], v[4:5]
	v_pk_mul_f32 v[8:9], v[8:9], v[134:135]
	s_cbranch_vccnz .LBB0_3768
	s_barrier
